# vC plus sc1 write-through on attention-output stores and on the out/down-proj residual epilogue stores only (cheaper L2 write-back at the following grid barrier)
# baseline (speedup 1.0000x reference)
; __device__ __forceinline__ unsigned cvt_pk_bf16(float lo, float hi) { unsigned r; asm volatile("v_cvt_pk_bf16_f32 %0, %1, %2" : "=v"(r) : "v"(lo), "v"(hi)); return r; }
; __device__ __forceinline__ void attn_finish(f32x16 (&o)[4], float l, LAS float* red, int w, int lane, bf16_t* outp  ) {
;     ...
;     float tot = 0.f;
; #pragma unroll
;     for (int w2 = 0; w2 < 8; ++w2) tot += red[w2 * 32 + ql];
;     const float rstd = __builtin_amdgcn_rsqf(tot * (1.0f / 1024.0f) + EPS);
; #pragma unroll
;     for (int db = 0; db < 4; ++db)
; #pragma unroll
;         for (int gp = 0; gp < 2; ++gp) {
;             u32x2 a, b;
;             a.x = cvt_pk_bf16(o[db][8 * gp + 0] * rstd, o[db][8 * gp + 1] * rstd); a.y = cvt_pk_bf16(o[db][8 * gp + 2] * rstd, o[db][8 * gp + 3] * rstd);
;             b.x = cvt_pk_bf16(o[db][8 * gp + 4] * rstd, o[db][8 * gp + 5] * rstd); b.y = cvt_pk_bf16(o[db][8 * gp + 6] * rstd, o[db][8 * gp + 7] * rstd);
;             const unsigned sx = hi ? a.x : b.x, sy = hi ? a.y : b.y;
;             const unsigned rx = __builtin_amdgcn_ds_bpermute((lane ^ 32) << 2, (int)sx), ry = __builtin_amdgcn_ds_bpermute((lane ^ 32) << 2, (int)sy);
;             u32x4 w4;
;             if (hi == 0) { w4.x = a.x; w4.y = a.y; w4.z = rx; w4.w = ry; } else { w4.x = rx; w4.y = ry; w4.z = b.x; w4.w = b.y; }
;             *(u32x4*)(outp + 32 * db + 16 * gp + 8 * hi) = w4;
;         }
.LBB0_138:
	s_or_b64 exec, exec, s[12:13]
	v_lshl_add_u32 v19, v212, 2, s21
	s_waitcnt lgkmcnt(0)
	s_barrier
	ds_read2_b32 v[20:21], v19 offset1:32
	v_lshlrev_b64 v[2:3], 12, v[200:201]
	v_lshl_add_u64 v[2:3], v[196:197], 0, v[2:3]
	s_waitcnt lgkmcnt(0)
	v_add_f32_e32 v20, 0, v20
	v_add_f32_e32 v22, v20, v21
	ds_read2_b32 v[20:21], v19 offset0:64 offset1:96
	s_waitcnt lgkmcnt(0)
	v_add_f32_e32 v20, v22, v20
	v_add_f32_e32 v22, v20, v21
	ds_read2_b32 v[20:21], v19 offset0:128 offset1:160
	s_waitcnt lgkmcnt(0)
	v_add_f32_e32 v20, v22, v20
	v_add_f32_e32 v22, v20, v21
	ds_read2_b32 v[20:21], v19 offset0:192 offset1:224
	s_waitcnt lgkmcnt(0)
	v_add_f32_e32 v19, v22, v20
	v_add_f32_e32 v19, v19, v21
	v_fmamk_f32 v19, v19, 0x3a800000, v207
	v_rsq_f32_e32 v19, v19
	s_nop 0
	v_mul_f32_e32 v20, v80, v19
	v_mul_f32_e32 v21, v81, v19
	v_cvt_pk_bf16_f32 v20, v20, v21
	v_mul_f32_e32 v21, v82, v19
	v_mul_f32_e32 v22, v83, v19
	v_cvt_pk_bf16_f32 v21, v21, v22
	v_mul_f32_e32 v22, v84, v19
	v_mul_f32_e32 v23, v85, v19
	v_cvt_pk_bf16_f32 v22, v22, v23
	v_mul_f32_e32 v23, v86, v19
	v_mul_f32_e32 v24, v87, v19
	v_cvt_pk_bf16_f32 v23, v23, v24
	v_cndmask_b32_e64 v24, v20, v22, s[36:37]
	v_cndmask_b32_e64 v25, v21, v23, s[36:37]
	ds_bpermute_b32 v24, v214, v24
	ds_bpermute_b32 v25, v214, v25
	v_mul_f32_e32 v11, v11, v19
	v_mul_f32_e32 v12, v12, v19
	v_mul_f32_e32 v0, v0, v19
	s_waitcnt lgkmcnt(1)
	v_cndmask_b32_e64 v22, v22, v24, s[36:37]
	v_cndmask_b32_e64 v20, v24, v20, s[36:37]
	s_waitcnt lgkmcnt(0)
	v_cndmask_b32_e64 v23, v23, v25, s[36:37]
	v_cndmask_b32_e64 v21, v25, v21, s[36:37]
	global_store_dwordx4 v[2:3], v[20:23], off sc1
	v_mul_f32_e32 v24, v79, v19
	v_mul_f32_e32 v4, v4, v19
	v_mul_f32_e32 v20, v70, v19
	v_mul_f32_e32 v21, v72, v19
	v_cvt_pk_bf16_f32 v20, v20, v21
	v_mul_f32_e32 v21, v74, v19
	v_mul_f32_e32 v22, v75, v19
	v_cvt_pk_bf16_f32 v21, v21, v22
	v_mul_f32_e32 v22, v76, v19
	v_mul_f32_e32 v23, v77, v19
	v_cvt_pk_bf16_f32 v22, v22, v23
	v_mul_f32_e32 v23, v78, v19
	v_cvt_pk_bf16_f32 v23, v23, v24
	v_cndmask_b32_e64 v24, v20, v22, s[36:37]
	v_cndmask_b32_e64 v25, v21, v23, s[36:37]
	ds_bpermute_b32 v24, v214, v24
	ds_bpermute_b32 v25, v214, v25
	s_waitcnt lgkmcnt(1)
	v_cndmask_b32_e64 v22, v22, v24, s[36:37]
	v_cndmask_b32_e64 v20, v24, v20, s[36:37]
	s_waitcnt lgkmcnt(0)
	v_cndmask_b32_e64 v23, v23, v25, s[36:37]
	v_cndmask_b32_e64 v21, v25, v21, s[36:37]
	global_store_dwordx4 v[2:3], v[20:23], off offset:32 sc1
	v_mul_f32_e32 v24, v73, v19
	s_nop 0
	v_mul_f32_e32 v20, v64, v19
	v_mul_f32_e32 v21, v65, v19
	v_cvt_pk_bf16_f32 v20, v20, v21
	v_mul_f32_e32 v21, v66, v19
	v_mul_f32_e32 v22, v67, v19
	v_cvt_pk_bf16_f32 v21, v21, v22
	v_mul_f32_e32 v22, v68, v19
	v_mul_f32_e32 v23, v69, v19
	v_cvt_pk_bf16_f32 v22, v22, v23
	v_mul_f32_e32 v23, v71, v19
	v_cvt_pk_bf16_f32 v23, v23, v24
	v_cndmask_b32_e64 v24, v20, v22, s[36:37]
	v_cndmask_b32_e64 v25, v21, v23, s[36:37]
	ds_bpermute_b32 v24, v214, v24
	ds_bpermute_b32 v25, v214, v25
	s_waitcnt lgkmcnt(1)
	v_cndmask_b32_e64 v22, v22, v24, s[36:37]
	v_cndmask_b32_e64 v20, v24, v20, s[36:37]
	s_waitcnt lgkmcnt(0)
	v_cndmask_b32_e64 v23, v23, v25, s[36:37]
	v_cndmask_b32_e64 v21, v25, v21, s[36:37]
	global_store_dwordx4 v[2:3], v[20:23], off offset:64 sc1
	v_mul_f32_e32 v24, v63, v19
	s_nop 0
	v_mul_f32_e32 v20, v54, v19
	v_mul_f32_e32 v21, v56, v19
	v_cvt_pk_bf16_f32 v20, v20, v21
	v_mul_f32_e32 v21, v58, v19
	v_mul_f32_e32 v22, v59, v19
	v_cvt_pk_bf16_f32 v21, v21, v22
	v_mul_f32_e32 v22, v60, v19
	v_mul_f32_e32 v23, v61, v19
	v_cvt_pk_bf16_f32 v22, v22, v23
	v_mul_f32_e32 v23, v62, v19
	v_cvt_pk_bf16_f32 v23, v23, v24
	v_cndmask_b32_e64 v24, v20, v22, s[36:37]
	v_cndmask_b32_e64 v25, v21, v23, s[36:37]
	ds_bpermute_b32 v24, v214, v24
	ds_bpermute_b32 v25, v214, v25
	s_waitcnt lgkmcnt(1)
	v_cndmask_b32_e64 v22, v22, v24, s[36:37]
	v_cndmask_b32_e64 v20, v24, v20, s[36:37]
	s_waitcnt lgkmcnt(0)
	v_cndmask_b32_e64 v23, v23, v25, s[36:37]
	v_cndmask_b32_e64 v21, v25, v21, s[36:37]
	global_store_dwordx4 v[2:3], v[20:23], off offset:96 sc1
	v_mul_f32_e32 v24, v57, v19
	s_nop 0
	v_mul_f32_e32 v20, v48, v19
	v_mul_f32_e32 v21, v49, v19
	v_cvt_pk_bf16_f32 v20, v20, v21
	v_mul_f32_e32 v21, v50, v19
	v_mul_f32_e32 v22, v51, v19
	v_cvt_pk_bf16_f32 v21, v21, v22
	v_mul_f32_e32 v22, v52, v19
	v_mul_f32_e32 v23, v53, v19
	v_cvt_pk_bf16_f32 v22, v22, v23
	v_mul_f32_e32 v23, v55, v19
	v_cvt_pk_bf16_f32 v23, v23, v24
	v_cndmask_b32_e64 v24, v20, v22, s[36:37]
	v_cndmask_b32_e64 v25, v21, v23, s[36:37]
	ds_bpermute_b32 v24, v214, v24
	ds_bpermute_b32 v25, v214, v25
	s_waitcnt lgkmcnt(1)
	v_cndmask_b32_e64 v22, v22, v24, s[36:37]
	v_cndmask_b32_e64 v20, v24, v20, s[36:37]
	s_waitcnt lgkmcnt(0)
	v_cndmask_b32_e64 v23, v23, v25, s[36:37]
	v_cndmask_b32_e64 v21, v25, v21, s[36:37]
	global_store_dwordx4 v[2:3], v[20:23], off offset:128 sc1
	v_mul_f32_e32 v24, v39, v19
	s_nop 0
	v_mul_f32_e32 v20, v32, v19
	v_mul_f32_e32 v21, v33, v19
	v_cvt_pk_bf16_f32 v20, v20, v21
	v_mul_f32_e32 v21, v34, v19
	v_mul_f32_e32 v22, v35, v19
	v_cvt_pk_bf16_f32 v21, v21, v22
	v_mul_f32_e32 v22, v36, v19
	v_mul_f32_e32 v23, v37, v19
	v_cvt_pk_bf16_f32 v22, v22, v23
	v_mul_f32_e32 v23, v38, v19
	v_cvt_pk_bf16_f32 v23, v23, v24
	v_cndmask_b32_e64 v24, v20, v22, s[36:37]
	v_cndmask_b32_e64 v25, v21, v23, s[36:37]
	ds_bpermute_b32 v24, v214, v24
	ds_bpermute_b32 v25, v214, v25
	s_waitcnt lgkmcnt(1)
	v_cndmask_b32_e64 v22, v22, v24, s[36:37]
	v_cndmask_b32_e64 v20, v24, v20, s[36:37]
	s_waitcnt lgkmcnt(0)
	v_cndmask_b32_e64 v23, v23, v25, s[36:37]
	v_cndmask_b32_e64 v21, v25, v21, s[36:37]
	global_store_dwordx4 v[2:3], v[20:23], off offset:160 sc1
	v_cvt_pk_bf16_f32 v11, v11, v12
	v_mul_f32_e32 v12, v13, v19
	v_mul_f32_e32 v13, v14, v19
	v_cvt_pk_bf16_f32 v13, v12, v13
	v_mul_f32_e32 v12, v15, v19
	v_mul_f32_e32 v14, v16, v19
	v_cvt_pk_bf16_f32 v12, v12, v14
	v_mul_f32_e32 v14, v17, v19
	v_mul_f32_e32 v15, v18, v19
	v_cvt_pk_bf16_f32 v15, v14, v15
	v_cndmask_b32_e64 v14, v11, v12, s[36:37]
	v_cndmask_b32_e64 v16, v13, v15, s[36:37]
	ds_bpermute_b32 v17, v214, v14
	ds_bpermute_b32 v16, v214, v16
	s_waitcnt lgkmcnt(1)
	v_cndmask_b32_e64 v14, v12, v17, s[36:37]
	v_cndmask_b32_e64 v12, v17, v11, s[36:37]
	s_waitcnt lgkmcnt(0)
	v_cndmask_b32_e64 v15, v15, v16, s[36:37]
	v_cndmask_b32_e64 v13, v16, v13, s[36:37]
	global_store_dwordx4 v[2:3], v[12:15], off offset:192 sc1
	v_cvt_pk_bf16_f32 v0, v0, v4
	v_mul_f32_e32 v4, v5, v19
	v_mul_f32_e32 v5, v6, v19
	v_cvt_pk_bf16_f32 v4, v4, v5
	v_mul_f32_e32 v5, v7, v19
	v_mul_f32_e32 v6, v8, v19
	v_cvt_pk_bf16_f32 v5, v5, v6
	v_mul_f32_e32 v6, v9, v19
	v_mul_f32_e32 v7, v10, v19
	v_cvt_pk_bf16_f32 v6, v6, v7
	v_cndmask_b32_e64 v7, v0, v5, s[36:37]
	v_cndmask_b32_e64 v8, v4, v6, s[36:37]
	ds_bpermute_b32 v7, v214, v7
	ds_bpermute_b32 v8, v214, v8
; __device__ __forceinline__ unsigned cvt_pk_bf16(float lo, float hi) { unsigned r; asm volatile("v_cvt_pk_bf16_f32 %0, %1, %2" : "=v"(r) : "v"(lo), "v"(hi)); return r; }
; __device__ __forceinline__ void attn_finish(f32x16 (&o)[4], float l, LAS float* red, int w, int lane, bf16_t* outp  ) {
;     ...
;             a.x = cvt_pk_bf16(o[db][8 * gp + 0] * rstd, o[db][8 * gp + 1] * rstd); a.y = cvt_pk_bf16(o[db][8 * gp + 2] * rstd, o[db][8 * gp + 3] * rstd);
;             b.x = cvt_pk_bf16(o[db][8 * gp + 4] * rstd, o[db][8 * gp + 5] * rstd); b.y = cvt_pk_bf16(o[db][8 * gp + 6] * rstd, o[db][8 * gp + 7] * rstd);
;             const unsigned sx = hi ? a.x : b.x, sy = hi ? a.y : b.y;
;             const unsigned rx = __builtin_amdgcn_ds_bpermute((lane ^ 32) << 2, (int)sx), ry = __builtin_amdgcn_ds_bpermute((lane ^ 32) << 2, (int)sy);
;             u32x4 w4;
;             if (hi == 0) { w4.x = a.x; w4.y = a.y; w4.z = rx; w4.w = ry; } else { w4.x = rx; w4.y = ry; w4.z = b.x; w4.w = b.y; }
;             *(u32x4*)(outp + 32 * db + 16 * gp + 8 * hi) = w4;
; __global__ void __launch_bounds__(NTHREADS, 2) fwd_kernel(Args a) {
;     ...
;             for (int u0 = bid; u0 < 512; u0 += G, ++ucount) {
.LBB0_139:
	s_add_i32 s20, s20, s86
	s_add_i32 s17, s17, 1
	s_waitcnt lgkmcnt(0)
	v_cndmask_b32_e64 v11, v6, v8, s[36:37]
	v_cndmask_b32_e64 v10, v5, v7, s[36:37]
	v_cndmask_b32_e64 v9, v8, v4, s[36:37]
	v_cndmask_b32_e64 v8, v7, v0, s[36:37]
	s_cmpk_gt_i32 s20, 0x1ff
	global_store_dwordx4 v[2:3], v[8:11], off offset:224 sc1
	s_cbranch_scc1 .LBB0_167

; __device__ __forceinline__ unsigned cvt_pk_bf16(float lo, float hi) { unsigned r; asm volatile("v_cvt_pk_bf16_f32 %0, %1, %2" : "=v"(r) : "v"(lo), "v"(hi)); return r; }
; __device__ __forceinline__ void attn_finish(f32x16 (&o)[4], float l, LAS float* red, int w, int lane, bf16_t* outp  ) {
;     ...
;     float tot = 0.f;
; #pragma unroll
;     for (int w2 = 0; w2 < 8; ++w2) tot += red[w2 * 32 + ql];
;     const float rstd = __builtin_amdgcn_rsqf(tot * (1.0f / 1024.0f) + EPS);
; #pragma unroll
;     for (int db = 0; db < 4; ++db)
; #pragma unroll
;         for (int gp = 0; gp < 2; ++gp) {
;             u32x2 a, b;
;             a.x = cvt_pk_bf16(o[db][8 * gp + 0] * rstd, o[db][8 * gp + 1] * rstd); a.y = cvt_pk_bf16(o[db][8 * gp + 2] * rstd, o[db][8 * gp + 3] * rstd);
;             b.x = cvt_pk_bf16(o[db][8 * gp + 4] * rstd, o[db][8 * gp + 5] * rstd); b.y = cvt_pk_bf16(o[db][8 * gp + 6] * rstd, o[db][8 * gp + 7] * rstd);
;             const unsigned sx = hi ? a.x : b.x, sy = hi ? a.y : b.y;
;             const unsigned rx = __builtin_amdgcn_ds_bpermute((lane ^ 32) << 2, (int)sx), ry = __builtin_amdgcn_ds_bpermute((lane ^ 32) << 2, (int)sy);
;             u32x4 w4;
;             if (hi == 0) { w4.x = a.x; w4.y = a.y; w4.z = rx; w4.w = ry; } else { w4.x = rx; w4.y = ry; w4.z = b.x; w4.w = b.y; }
;             *(u32x4*)(outp + 32 * db + 16 * gp + 8 * hi) = w4;
;         }
.LBB0_157:
	s_or_b64 exec, exec, s[12:13]
	v_lshl_add_u32 v16, v212, 2, s21
	s_waitcnt lgkmcnt(0)
	s_barrier
	ds_read2_b32 v[10:11], v16 offset1:32
	ds_read2_b32 v[12:13], v16 offset0:64 offset1:96
	ds_read2_b32 v[14:15], v16 offset0:128 offset1:160
	s_mov_b64 s[12:13], 0x800
	s_waitcnt lgkmcnt(2)
	v_add_f32_e32 v10, 0, v10
	v_add_f32_e32 v17, v10, v11
	ds_read2_b32 v[10:11], v16 offset0:192 offset1:224
	s_waitcnt lgkmcnt(2)
	v_add_f32_e32 v12, v17, v12
	v_add_f32_e32 v12, v12, v13
	s_waitcnt lgkmcnt(1)
	v_add_f32_e32 v12, v12, v14
	v_add_f32_e32 v12, v12, v15
	s_waitcnt lgkmcnt(0)
	v_add_f32_e32 v10, v12, v10
	v_add_f32_e32 v10, v10, v11
	v_fmamk_f32 v10, v10, 0x3a800000, v207
	v_rsq_f32_e32 v16, v10
	s_nop 0
	v_mul_f32_e32 v10, v66, v16
	v_mul_f32_e32 v11, v67, v16
	v_cvt_pk_bf16_f32 v13, v10, v11
	v_mul_f32_e32 v10, v68, v16
	v_mul_f32_e32 v11, v69, v16
	v_cvt_pk_bf16_f32 v17, v10, v11
	v_mul_f32_e32 v10, v70, v16
	v_mul_f32_e32 v11, v71, v16
	v_cvt_pk_bf16_f32 v12, v10, v11
	v_mul_f32_e32 v10, v72, v16
	v_mul_f32_e32 v11, v73, v16
	v_cvt_pk_bf16_f32 v66, v10, v11
	v_cndmask_b32_e64 v10, v13, v12, s[36:37]
	ds_bpermute_b32 v67, v214, v10
	v_cndmask_b32_e64 v10, v17, v66, s[36:37]
	ds_bpermute_b32 v68, v214, v10
	v_lshlrev_b64 v[10:11], 12, v[0:1]
	v_lshl_add_u64 v[14:15], v[196:197], 0, v[10:11]
	s_waitcnt lgkmcnt(1)
	v_cndmask_b32_e64 v12, v12, v67, s[36:37]
	v_cndmask_b32_e64 v10, v67, v13, s[36:37]
	s_waitcnt lgkmcnt(0)
	v_cndmask_b32_e64 v13, v66, v68, s[36:37]
	v_cndmask_b32_e64 v11, v68, v17, s[36:37]
	global_store_dwordx4 v[14:15], v[10:13], off offset:2048 sc1
	v_mul_f32_e32 v0, v51, v16
	s_nop 0
	v_mul_f32_e32 v10, v54, v16
	v_cvt_pk_bf16_f32 v0, v0, v10
	v_mul_f32_e32 v10, v55, v16
	v_mul_f32_e32 v11, v58, v16
	v_cvt_pk_bf16_f32 v11, v10, v11
	v_mul_f32_e32 v10, v59, v16
	v_mul_f32_e32 v12, v62, v16
	v_cvt_pk_bf16_f32 v10, v10, v12
	v_mul_f32_e32 v12, v63, v16
	v_mul_f32_e32 v13, v65, v16
	v_cvt_pk_bf16_f32 v13, v12, v13
	v_cndmask_b32_e64 v12, v0, v10, s[36:37]
	ds_bpermute_b32 v17, v214, v12
	v_cndmask_b32_e64 v12, v11, v13, s[36:37]
	ds_bpermute_b32 v51, v214, v12
	s_waitcnt lgkmcnt(1)
	v_cndmask_b32_e64 v12, v10, v17, s[36:37]
	v_cndmask_b32_e64 v10, v17, v0, s[36:37]
	s_waitcnt lgkmcnt(0)
	v_cndmask_b32_e64 v13, v13, v51, s[36:37]
	v_cndmask_b32_e64 v11, v51, v11, s[36:37]
	global_store_dwordx4 v[14:15], v[10:13], off offset:2080 sc1
	v_mul_f32_e32 v0, v50, v16
	s_nop 0
	v_mul_f32_e32 v10, v52, v16
	v_cvt_pk_bf16_f32 v0, v0, v10
	v_mul_f32_e32 v10, v53, v16
	v_mul_f32_e32 v11, v56, v16
	v_cvt_pk_bf16_f32 v11, v10, v11
	v_mul_f32_e32 v10, v57, v16
	v_mul_f32_e32 v12, v60, v16
	v_cvt_pk_bf16_f32 v10, v10, v12
	v_mul_f32_e32 v12, v61, v16
	v_mul_f32_e32 v13, v64, v16
	v_cvt_pk_bf16_f32 v13, v12, v13
	v_cndmask_b32_e64 v12, v0, v10, s[36:37]
	ds_bpermute_b32 v17, v214, v12
	v_cndmask_b32_e64 v12, v11, v13, s[36:37]
	ds_bpermute_b32 v50, v214, v12
	s_waitcnt lgkmcnt(1)
	v_cndmask_b32_e64 v12, v10, v17, s[36:37]
	v_cndmask_b32_e64 v10, v17, v0, s[36:37]
	s_waitcnt lgkmcnt(0)
	v_cndmask_b32_e64 v13, v13, v50, s[36:37]
	v_cndmask_b32_e64 v11, v50, v11, s[36:37]
	global_store_dwordx4 v[14:15], v[10:13], off offset:2112 sc1
	v_mul_f32_e32 v0, v35, v16
	s_nop 0
	v_mul_f32_e32 v10, v38, v16
	v_cvt_pk_bf16_f32 v0, v0, v10
	v_mul_f32_e32 v10, v39, v16
	v_mul_f32_e32 v11, v42, v16
	v_cvt_pk_bf16_f32 v11, v10, v11
	v_mul_f32_e32 v10, v43, v16
	v_mul_f32_e32 v12, v46, v16
	v_cvt_pk_bf16_f32 v10, v10, v12
	v_mul_f32_e32 v12, v47, v16
	v_mul_f32_e32 v13, v49, v16
	v_cvt_pk_bf16_f32 v13, v12, v13
	v_cndmask_b32_e64 v12, v0, v10, s[36:37]
	ds_bpermute_b32 v17, v214, v12
	v_cndmask_b32_e64 v12, v11, v13, s[36:37]
	ds_bpermute_b32 v35, v214, v12
	s_waitcnt lgkmcnt(1)
	v_cndmask_b32_e64 v12, v10, v17, s[36:37]
	v_cndmask_b32_e64 v10, v17, v0, s[36:37]
	s_waitcnt lgkmcnt(0)
	v_cndmask_b32_e64 v13, v13, v35, s[36:37]
	v_cndmask_b32_e64 v11, v35, v11, s[36:37]
	global_store_dwordx4 v[14:15], v[10:13], off offset:2144 sc1
	v_mul_f32_e32 v0, v34, v16
	s_nop 0
	v_mul_f32_e32 v10, v36, v16
	v_cvt_pk_bf16_f32 v0, v0, v10
	v_mul_f32_e32 v10, v37, v16
	v_mul_f32_e32 v11, v40, v16
	v_cvt_pk_bf16_f32 v11, v10, v11
	v_mul_f32_e32 v10, v41, v16
	v_mul_f32_e32 v12, v44, v16
	v_cvt_pk_bf16_f32 v10, v10, v12
	v_mul_f32_e32 v12, v45, v16
	v_mul_f32_e32 v13, v48, v16
	v_cvt_pk_bf16_f32 v13, v12, v13
	v_cndmask_b32_e64 v12, v0, v10, s[36:37]
	ds_bpermute_b32 v17, v214, v12
	v_cndmask_b32_e64 v12, v11, v13, s[36:37]
	ds_bpermute_b32 v34, v214, v12
	s_waitcnt lgkmcnt(1)
	v_cndmask_b32_e64 v12, v10, v17, s[36:37]
	v_cndmask_b32_e64 v10, v17, v0, s[36:37]
	s_waitcnt lgkmcnt(0)
	v_cndmask_b32_e64 v13, v13, v34, s[36:37]
	v_cndmask_b32_e64 v11, v34, v11, s[36:37]
	global_store_dwordx4 v[14:15], v[10:13], off offset:2176 sc1
	v_mul_f32_e32 v0, v19, v16
	s_nop 0
	v_mul_f32_e32 v10, v22, v16
	v_cvt_pk_bf16_f32 v0, v0, v10
	v_mul_f32_e32 v10, v23, v16
	v_mul_f32_e32 v11, v26, v16
	v_cvt_pk_bf16_f32 v11, v10, v11
	v_mul_f32_e32 v10, v27, v16
	v_mul_f32_e32 v12, v30, v16
	v_cvt_pk_bf16_f32 v10, v10, v12
	v_mul_f32_e32 v12, v31, v16
	v_mul_f32_e32 v13, v33, v16
	v_cvt_pk_bf16_f32 v13, v12, v13
	v_cndmask_b32_e64 v12, v0, v10, s[36:37]
	ds_bpermute_b32 v17, v214, v12
	v_cndmask_b32_e64 v12, v11, v13, s[36:37]
	ds_bpermute_b32 v19, v214, v12
	s_waitcnt lgkmcnt(1)
	v_cndmask_b32_e64 v12, v10, v17, s[36:37]
	v_cndmask_b32_e64 v10, v17, v0, s[36:37]
	s_waitcnt lgkmcnt(0)
	v_cndmask_b32_e64 v13, v13, v19, s[36:37]
	v_cndmask_b32_e64 v11, v19, v11, s[36:37]
	global_store_dwordx4 v[14:15], v[10:13], off offset:2208 sc1
	v_mul_f32_e32 v0, v18, v16
	s_nop 0
	v_mul_f32_e32 v10, v20, v16
	v_cvt_pk_bf16_f32 v0, v0, v10
	v_mul_f32_e32 v10, v21, v16
	v_mul_f32_e32 v11, v24, v16
	v_cvt_pk_bf16_f32 v11, v10, v11
	v_mul_f32_e32 v10, v25, v16
	v_mul_f32_e32 v12, v28, v16
	v_cvt_pk_bf16_f32 v10, v10, v12
	v_mul_f32_e32 v12, v29, v16
	v_mul_f32_e32 v13, v32, v16
	v_cvt_pk_bf16_f32 v13, v12, v13
	v_cndmask_b32_e64 v12, v0, v10, s[36:37]
	ds_bpermute_b32 v17, v214, v12
	v_cndmask_b32_e64 v12, v11, v13, s[36:37]
	ds_bpermute_b32 v18, v214, v12
	s_waitcnt lgkmcnt(1)
	v_cndmask_b32_e64 v12, v10, v17, s[36:37]
	v_cndmask_b32_e64 v10, v17, v0, s[36:37]
	s_waitcnt lgkmcnt(0)
	v_cndmask_b32_e64 v13, v13, v18, s[36:37]
	v_cndmask_b32_e64 v11, v18, v11, s[36:37]
	v_mul_f32_e32 v0, v2, v16
	v_mul_f32_e32 v2, v3, v16
	global_store_dwordx4 v[14:15], v[10:13], off offset:2240 sc1
	v_cvt_pk_bf16_f32 v0, v0, v2
	v_mul_f32_e32 v2, v4, v16
	v_mul_f32_e32 v3, v5, v16
	v_cvt_pk_bf16_f32 v4, v2, v3
	v_mul_f32_e32 v2, v6, v16
	v_mul_f32_e32 v3, v7, v16
	v_cvt_pk_bf16_f32 v5, v2, v3
	v_mul_f32_e32 v2, v8, v16
	v_mul_f32_e32 v3, v9, v16
	v_cvt_pk_bf16_f32 v6, v2, v3
	v_cndmask_b32_e64 v2, v0, v5, s[36:37]
	v_cndmask_b32_e64 v3, v4, v6, s[36:37]
	ds_bpermute_b32 v7, v214, v2
	ds_bpermute_b32 v8, v214, v3
	v_lshl_add_u64 v[2:3], v[14:15], 0, s[12:13]
	s_mov_b64 s[12:13], 0

; __device__ __forceinline__ unsigned cvt_pk_bf16(float lo, float hi) { unsigned r; asm volatile("v_cvt_pk_bf16_f32 %0, %1, %2" : "=v"(r) : "v"(lo), "v"(hi)); return r; }
; __device__ __forceinline__ float bflo(unsigned u) { return __uint_as_float(u << 16); }
; __device__ __forceinline__ float bfhi(unsigned u) { return __uint_as_float(u & 0xffff0000u); }
; __device__ __forceinline__ float shfl_xor_l(float v, int mask, int lane) { return __builtin_bit_cast(float, __builtin_amdgcn_ds_bpermute((lane ^ mask) << 2, __builtin_bit_cast(int, v))); }
; template <bool F32OUT>
; __device__ __forceinline__ void res_epi(const f32x4 (&acc)[2][2][4][2], int pm, int pn, int wr, int wc, int fr, int fq, bf16_t* xb, float* xout, float* ssq_next) {
;     ...
;             const int row = row0 + ai * HALF + m * 16;
;             const size_t off = (size_t)row * D + col0;
;             u32x4 r[2];
; #pragma unroll
;             for (int bj = 0; bj < 2; ++bj) r[bj] = *(const u32x4*)(xb + off + bj * HALF);
;             float s = 0.f;
; #pragma unroll
;             for (int bj = 0; bj < 2; ++bj) {
;                 f32x4 v0 = acc[ai][bj][m][0], v1 = acc[ai][bj][m][1];
;                 v0[0] += bflo(r[bj].x); v0[1] += bfhi(r[bj].x); v0[2] += bflo(r[bj].y); v0[3] += bfhi(r[bj].y);
;                 v1[0] += bflo(r[bj].z); v1[1] += bfhi(r[bj].z); v1[2] += bflo(r[bj].w); v1[3] += bfhi(r[bj].w);
;                 if (F32OUT) { *(f32x4*)(xout + off + bj * HALF) = v0; *(f32x4*)(xout + off + bj * HALF + 4) = v1; }
;                 s += ((v0[0] * v0[0] + v0[1] * v0[1]) + (v0[2] * v0[2] + v0[3] * v0[3])) + ((v1[0] * v1[0] + v1[1] * v1[1]) + (v1[2] * v1[2] + v1[3] * v1[3]));
;                 u32x4 w; w.x = cvt_pk_bf16(v0[0], v0[1]); w.y = cvt_pk_bf16(v0[2], v0[3]); w.z = cvt_pk_bf16(v1[0], v1[1]); w.w = cvt_pk_bf16(v1[2], v1[3]);
;                 if (!F32OUT) *(u32x4*)(xb + off + bj * HALF) = w;
;             }
;             if (!F32OUT) { s += shfl_xor_l(s, 16, ln); s += shfl_xor_l(s, 32, ln);
;                 ssq_next[(size_t)row * 32 + pn * 4 + wc] = s; }
.LBB0_258:
	s_andn2_b64 vcc, exec, s[0:1]
	s_cbranch_vccnz .LBB0_260
	s_lshl_b32 s0, s27, 8
	s_add_i32 s0, s0, s53
	v_or_b32_e32 v130, s0, v213
	s_lshl_b32 s0, s22, 8
	v_lshl_or_b32 v0, v214, 3, s0
	v_lshlrev_b32_e32 v131, 6, v214
	v_lshlrev_b32_e32 v134, 2, v213
	s_movk_i32 s0, 0x80
	v_or_b32_e32 v132, s50, v0
	v_bitop3_b32 v0, v131, 64, v134 bitop3:0x36
	v_bitop3_b32 v134, v131, s0, v134 bitop3:0x36
	v_ashrrev_i32_e32 v131, 31, v130
	v_ashrrev_i32_e32 v133, 31, v132
	v_lshlrev_b64 v[136:137], 12, v[130:131]
	v_lshl_add_u64 v[136:137], s[4:5], 0, v[136:137]
	v_lshlrev_b64 v[132:133], 1, v[132:133]
	v_lshl_add_u64 v[144:145], v[136:137], 0, v[132:133]
	global_load_dwordx4 v[136:139], v[144:145], off
	global_load_dwordx4 v[140:143], v[144:145], off offset:256
	s_lshl_b32 s0, s22, 2
	s_ashr_i32 s1, s0, 31
	s_lshl_b64 s[0:1], s[0:1], 2
	v_readlane_b32 s16, v236, 52
	s_add_u32 s0, s16, s0
	v_readlane_b32 s16, v236, 53
	s_addc_u32 s1, s16, s1
	s_waitcnt vmcnt(0)
	v_lshlrev_b32_e32 v135, 16, v136
	v_add_f32_e32 v126, v126, v135
	v_and_b32_e32 v135, 0xffff0000, v136
	v_add_f32_e32 v127, v127, v135
	v_lshlrev_b32_e32 v135, 16, v137
	v_add_f32_e32 v128, v128, v135
	v_and_b32_e32 v135, 0xffff0000, v137
	v_add_f32_e32 v129, v129, v135
	v_lshlrev_b32_e32 v135, 16, v138
	v_add_f32_e32 v135, v122, v135
	v_and_b32_e32 v122, 0xffff0000, v138
	v_add_f32_e32 v136, v123, v122
	v_lshlrev_b32_e32 v122, 16, v139
	v_add_f32_e32 v137, v124, v122
	v_and_b32_e32 v122, 0xffff0000, v139
	v_add_f32_e32 v125, v125, v122
	v_mul_f32_e32 v122, v127, v127
	v_mul_f32_e32 v123, v129, v129
	v_fmac_f32_e32 v122, v126, v126
	v_fmac_f32_e32 v123, v128, v128
	v_add_f32_e32 v122, v122, v123
	v_mul_f32_e32 v123, v136, v136
	v_mul_f32_e32 v124, v125, v125
	v_fmac_f32_e32 v123, v135, v135
	v_fmac_f32_e32 v124, v137, v137
	v_add_f32_e32 v123, v123, v124
	v_add_f32_e32 v138, v122, v123
	v_cvt_pk_bf16_f32 v122, v126, v127
	v_cvt_pk_bf16_f32 v123, v128, v129
	v_cvt_pk_bf16_f32 v124, v135, v136
	v_cvt_pk_bf16_f32 v125, v137, v125
	global_store_dwordx4 v[144:145], v[122:125], off sc1
	s_nop 1
	v_lshlrev_b32_e32 v122, 16, v140
	v_add_f32_e32 v118, v118, v122
	v_and_b32_e32 v122, 0xffff0000, v140
	v_add_f32_e32 v119, v119, v122
	v_lshlrev_b32_e32 v122, 16, v141
	v_add_f32_e32 v120, v120, v122
	v_and_b32_e32 v122, 0xffff0000, v141
	v_add_f32_e32 v121, v121, v122
	v_lshlrev_b32_e32 v122, 16, v142
	v_add_f32_e32 v122, v114, v122
	v_and_b32_e32 v114, 0xffff0000, v142
	v_add_f32_e32 v123, v115, v114
	v_lshlrev_b32_e32 v114, 16, v143
	v_add_f32_e32 v124, v116, v114
	v_and_b32_e32 v114, 0xffff0000, v143
	v_add_f32_e32 v117, v117, v114
	v_mul_f32_e32 v114, v119, v119
	v_mul_f32_e32 v115, v121, v121
	v_fmac_f32_e32 v114, v118, v118
	v_fmac_f32_e32 v115, v120, v120
	v_add_f32_e32 v114, v114, v115
	v_mul_f32_e32 v115, v123, v123
	v_mul_f32_e32 v116, v117, v117
	v_fmac_f32_e32 v115, v122, v122
	v_fmac_f32_e32 v116, v124, v124
	v_add_f32_e32 v115, v115, v116
	v_add_f32_e32 v114, v114, v115
	v_add_f32_e32 v125, v138, v114
	v_cvt_pk_bf16_f32 v114, v118, v119
	v_cvt_pk_bf16_f32 v115, v120, v121
	v_cvt_pk_bf16_f32 v116, v122, v123
	v_cvt_pk_bf16_f32 v117, v124, v117
	global_store_dwordx4 v[144:145], v[114:117], off offset:256 sc1
	ds_bpermute_b32 v114, v0, v125
	s_waitcnt lgkmcnt(0)
	v_add_f32_e32 v114, v125, v114
	ds_bpermute_b32 v115, v134, v114
	s_waitcnt lgkmcnt(0)
	v_add_f32_e32 v116, v114, v115
	v_lshlrev_b64 v[114:115], 7, v[130:131]
	v_lshl_add_u64 v[114:115], s[0:1], 0, v[114:115]
	global_store_dword v[114:115], v116, off
	v_or_b32_e32 v114, 16, v130
	v_ashrrev_i32_e32 v115, 31, v114
	v_lshlrev_b64 v[116:117], 12, v[114:115]
	v_lshl_add_u64 v[116:117], s[4:5], 0, v[116:117]
	v_lshl_add_u64 v[116:117], v[116:117], 0, v[132:133]
	global_load_dwordx4 v[118:121], v[116:117], off
	global_load_dwordx4 v[122:125], v[116:117], off offset:256
	s_waitcnt vmcnt(1)
	v_lshlrev_b32_e32 v126, 16, v118
	v_and_b32_e32 v118, 0xffff0000, v118
	v_add_f32_e32 v111, v111, v118
	v_lshlrev_b32_e32 v118, 16, v119
	v_add_f32_e32 v112, v112, v118
	v_and_b32_e32 v118, 0xffff0000, v119
	v_add_f32_e32 v113, v113, v118
	v_lshlrev_b32_e32 v118, 16, v120
	v_add_f32_e32 v118, v106, v118
	v_and_b32_e32 v106, 0xffff0000, v120
	v_add_f32_e32 v119, v107, v106
	v_lshlrev_b32_e32 v106, 16, v121
	v_add_f32_e32 v120, v108, v106
	v_and_b32_e32 v106, 0xffff0000, v121
	v_add_f32_e32 v110, v110, v126
	v_add_f32_e32 v109, v109, v106
	v_mul_f32_e32 v106, v111, v111
	v_mul_f32_e32 v107, v113, v113
	v_fmac_f32_e32 v106, v110, v110
	v_fmac_f32_e32 v107, v112, v112
	v_add_f32_e32 v106, v106, v107
	v_mul_f32_e32 v107, v119, v119
	v_mul_f32_e32 v108, v109, v109
	v_fmac_f32_e32 v107, v118, v118
	v_fmac_f32_e32 v108, v120, v120
	v_add_f32_e32 v107, v107, v108
	v_add_f32_e32 v121, v106, v107
	v_cvt_pk_bf16_f32 v106, v110, v111
	v_cvt_pk_bf16_f32 v107, v112, v113
	v_cvt_pk_bf16_f32 v108, v118, v119
	v_cvt_pk_bf16_f32 v109, v120, v109
	global_store_dwordx4 v[116:117], v[106:109], off sc1
	s_waitcnt vmcnt(1)
	s_nop 0
	v_lshlrev_b32_e32 v106, 16, v122
	v_add_f32_e32 v102, v102, v106
	v_and_b32_e32 v106, 0xffff0000, v122
	v_add_f32_e32 v103, v103, v106
	v_lshlrev_b32_e32 v106, 16, v123
	v_add_f32_e32 v104, v104, v106
	v_and_b32_e32 v106, 0xffff0000, v123
	v_add_f32_e32 v105, v105, v106
	v_lshlrev_b32_e32 v106, 16, v124
	v_add_f32_e32 v106, v98, v106
	v_and_b32_e32 v98, 0xffff0000, v124
	v_add_f32_e32 v107, v99, v98
	v_lshlrev_b32_e32 v98, 16, v125
	v_add_f32_e32 v108, v100, v98
	v_and_b32_e32 v98, 0xffff0000, v125
	v_add_f32_e32 v101, v101, v98
	v_mul_f32_e32 v98, v103, v103
	v_mul_f32_e32 v99, v105, v105
	v_fmac_f32_e32 v98, v102, v102
	v_fmac_f32_e32 v99, v104, v104
	v_add_f32_e32 v98, v98, v99
	v_mul_f32_e32 v99, v107, v107
	v_mul_f32_e32 v100, v101, v101
	v_fmac_f32_e32 v99, v106, v106
	v_fmac_f32_e32 v100, v108, v108
	v_add_f32_e32 v99, v99, v100
	v_add_f32_e32 v98, v98, v99
	v_add_f32_e32 v109, v121, v98
	v_cvt_pk_bf16_f32 v98, v102, v103
	v_cvt_pk_bf16_f32 v99, v104, v105
	v_cvt_pk_bf16_f32 v100, v106, v107
	v_cvt_pk_bf16_f32 v101, v108, v101
	global_store_dwordx4 v[116:117], v[98:101], off offset:256 sc1
	ds_bpermute_b32 v98, v0, v109
	s_waitcnt lgkmcnt(0)
; __device__ __forceinline__ unsigned cvt_pk_bf16(float lo, float hi) { unsigned r; asm volatile("v_cvt_pk_bf16_f32 %0, %1, %2" : "=v"(r) : "v"(lo), "v"(hi)); return r; }
; __device__ __forceinline__ float bflo(unsigned u) { return __uint_as_float(u << 16); }
; __device__ __forceinline__ float bfhi(unsigned u) { return __uint_as_float(u & 0xffff0000u); }
; __device__ __forceinline__ float shfl_xor_l(float v, int mask, int lane) { return __builtin_bit_cast(float, __builtin_amdgcn_ds_bpermute((lane ^ mask) << 2, __builtin_bit_cast(int, v))); }
; template <bool F32OUT>
; __device__ __forceinline__ void res_epi(const f32x4 (&acc)[2][2][4][2], int pm, int pn, int wr, int wc, int fr, int fq, bf16_t* xb, float* xout, float* ssq_next) {
;     ...
;             const int row = row0 + ai * HALF + m * 16;
;             const size_t off = (size_t)row * D + col0;
;             u32x4 r[2];
; #pragma unroll
;             for (int bj = 0; bj < 2; ++bj) r[bj] = *(const u32x4*)(xb + off + bj * HALF);
;             float s = 0.f;
; #pragma unroll
;             for (int bj = 0; bj < 2; ++bj) {
;                 f32x4 v0 = acc[ai][bj][m][0], v1 = acc[ai][bj][m][1];
;                 v0[0] += bflo(r[bj].x); v0[1] += bfhi(r[bj].x); v0[2] += bflo(r[bj].y); v0[3] += bfhi(r[bj].y);
;                 v1[0] += bflo(r[bj].z); v1[1] += bfhi(r[bj].z); v1[2] += bflo(r[bj].w); v1[3] += bfhi(r[bj].w);
;                 if (F32OUT) { *(f32x4*)(xout + off + bj * HALF) = v0; *(f32x4*)(xout + off + bj * HALF + 4) = v1; }
;                 s += ((v0[0] * v0[0] + v0[1] * v0[1]) + (v0[2] * v0[2] + v0[3] * v0[3])) + ((v1[0] * v1[0] + v1[1] * v1[1]) + (v1[2] * v1[2] + v1[3] * v1[3]));
;                 u32x4 w; w.x = cvt_pk_bf16(v0[0], v0[1]); w.y = cvt_pk_bf16(v0[2], v0[3]); w.z = cvt_pk_bf16(v1[0], v1[1]); w.w = cvt_pk_bf16(v1[2], v1[3]);
;                 if (!F32OUT) *(u32x4*)(xb + off + bj * HALF) = w;
;             }
;             if (!F32OUT) { s += shfl_xor_l(s, 16, ln); s += shfl_xor_l(s, 32, ln);
;                 ssq_next[(size_t)row * 32 + pn * 4 + wc] = s; }
	v_add_f32_e32 v98, v109, v98
	ds_bpermute_b32 v99, v134, v98
	s_waitcnt lgkmcnt(0)
	v_add_f32_e32 v100, v98, v99
	v_lshlrev_b64 v[98:99], 7, v[114:115]
	v_lshl_add_u64 v[98:99], s[0:1], 0, v[98:99]
	global_store_dword v[98:99], v100, off
	v_or_b32_e32 v98, 32, v130
	v_ashrrev_i32_e32 v99, 31, v98
	v_lshlrev_b64 v[100:101], 12, v[98:99]
	v_lshl_add_u64 v[100:101], s[4:5], 0, v[100:101]
	v_lshl_add_u64 v[100:101], v[100:101], 0, v[132:133]
	global_load_dwordx4 v[102:105], v[100:101], off
	global_load_dwordx4 v[106:109], v[100:101], off offset:256
	s_waitcnt vmcnt(1)
	v_lshlrev_b32_e32 v110, 16, v102
	v_and_b32_e32 v102, 0xffff0000, v102
	v_add_f32_e32 v95, v95, v102
	v_lshlrev_b32_e32 v102, 16, v103
	v_add_f32_e32 v96, v96, v102
	v_and_b32_e32 v102, 0xffff0000, v103
	v_add_f32_e32 v97, v97, v102
	v_lshlrev_b32_e32 v102, 16, v104
	v_add_f32_e32 v102, v90, v102
	v_and_b32_e32 v90, 0xffff0000, v104
	v_add_f32_e32 v103, v91, v90
	v_lshlrev_b32_e32 v90, 16, v105
	v_add_f32_e32 v104, v92, v90
	v_and_b32_e32 v90, 0xffff0000, v105
	v_add_f32_e32 v94, v94, v110
	v_add_f32_e32 v93, v93, v90
	v_mul_f32_e32 v90, v95, v95
	v_mul_f32_e32 v91, v97, v97
	v_fmac_f32_e32 v90, v94, v94
	v_fmac_f32_e32 v91, v96, v96
	v_add_f32_e32 v90, v90, v91
	v_mul_f32_e32 v91, v103, v103
	v_mul_f32_e32 v92, v93, v93
	v_fmac_f32_e32 v91, v102, v102
	v_fmac_f32_e32 v92, v104, v104
	v_add_f32_e32 v91, v91, v92
	v_add_f32_e32 v105, v90, v91
	v_cvt_pk_bf16_f32 v90, v94, v95
	v_cvt_pk_bf16_f32 v91, v96, v97
	v_cvt_pk_bf16_f32 v92, v102, v103
	v_cvt_pk_bf16_f32 v93, v104, v93
	global_store_dwordx4 v[100:101], v[90:93], off sc1
	s_waitcnt vmcnt(1)
	s_nop 0
	v_lshlrev_b32_e32 v90, 16, v106
	v_add_f32_e32 v86, v86, v90
	v_and_b32_e32 v90, 0xffff0000, v106
	v_add_f32_e32 v87, v87, v90
	v_lshlrev_b32_e32 v90, 16, v107
	v_add_f32_e32 v88, v88, v90
	v_and_b32_e32 v90, 0xffff0000, v107
	v_add_f32_e32 v89, v89, v90
	v_lshlrev_b32_e32 v90, 16, v108
	v_add_f32_e32 v90, v82, v90
	v_and_b32_e32 v82, 0xffff0000, v108
	v_add_f32_e32 v91, v83, v82
	v_lshlrev_b32_e32 v82, 16, v109
	v_add_f32_e32 v92, v84, v82
	v_and_b32_e32 v82, 0xffff0000, v109
	v_add_f32_e32 v85, v85, v82
	v_mul_f32_e32 v82, v87, v87
	v_mul_f32_e32 v83, v89, v89
	v_fmac_f32_e32 v82, v86, v86
	v_fmac_f32_e32 v83, v88, v88
	v_add_f32_e32 v82, v82, v83
	v_mul_f32_e32 v83, v91, v91
	v_mul_f32_e32 v84, v85, v85
	v_fmac_f32_e32 v83, v90, v90
	v_fmac_f32_e32 v84, v92, v92
	v_add_f32_e32 v83, v83, v84
	v_add_f32_e32 v82, v82, v83
	v_add_f32_e32 v93, v105, v82
	v_cvt_pk_bf16_f32 v82, v86, v87
	v_cvt_pk_bf16_f32 v83, v88, v89
	v_cvt_pk_bf16_f32 v84, v90, v91
	v_cvt_pk_bf16_f32 v85, v92, v85
	global_store_dwordx4 v[100:101], v[82:85], off offset:256 sc1
	ds_bpermute_b32 v82, v0, v93
	s_waitcnt lgkmcnt(0)
	v_add_f32_e32 v82, v93, v82
	ds_bpermute_b32 v83, v134, v82
	s_waitcnt lgkmcnt(0)
	v_add_f32_e32 v84, v82, v83
	v_lshlrev_b64 v[82:83], 7, v[98:99]
	v_lshl_add_u64 v[82:83], s[0:1], 0, v[82:83]
	global_store_dword v[82:83], v84, off
	v_or_b32_e32 v82, 48, v130
	v_ashrrev_i32_e32 v83, 31, v82
	v_lshlrev_b64 v[84:85], 12, v[82:83]
	v_lshl_add_u64 v[84:85], s[4:5], 0, v[84:85]
	v_lshl_add_u64 v[84:85], v[84:85], 0, v[132:133]
	global_load_dwordx4 v[86:89], v[84:85], off
	global_load_dwordx4 v[90:93], v[84:85], off offset:256
	s_waitcnt vmcnt(1)
	v_lshlrev_b32_e32 v94, 16, v86
	v_and_b32_e32 v86, 0xffff0000, v86
	v_add_f32_e32 v79, v79, v86
	v_lshlrev_b32_e32 v86, 16, v87
	v_add_f32_e32 v80, v80, v86
	v_and_b32_e32 v86, 0xffff0000, v87
	v_add_f32_e32 v81, v81, v86
	v_lshlrev_b32_e32 v86, 16, v88
	v_add_f32_e32 v86, v74, v86
	v_and_b32_e32 v74, 0xffff0000, v88
	v_add_f32_e32 v87, v75, v74
	v_lshlrev_b32_e32 v74, 16, v89
	v_add_f32_e32 v88, v76, v74
	v_and_b32_e32 v74, 0xffff0000, v89
	v_add_f32_e32 v78, v78, v94
	v_add_f32_e32 v77, v77, v74
	v_mul_f32_e32 v74, v79, v79
	v_mul_f32_e32 v75, v81, v81
	v_fmac_f32_e32 v74, v78, v78
	v_fmac_f32_e32 v75, v80, v80
	v_add_f32_e32 v74, v74, v75
	v_mul_f32_e32 v75, v87, v87
	v_mul_f32_e32 v76, v77, v77
	v_fmac_f32_e32 v75, v86, v86
	v_fmac_f32_e32 v76, v88, v88
	v_add_f32_e32 v75, v75, v76
	v_add_f32_e32 v89, v74, v75
	v_cvt_pk_bf16_f32 v74, v78, v79
	v_cvt_pk_bf16_f32 v75, v80, v81
	v_cvt_pk_bf16_f32 v76, v86, v87
	v_cvt_pk_bf16_f32 v77, v88, v77
	global_store_dwordx4 v[84:85], v[74:77], off sc1
	s_waitcnt vmcnt(1)
	s_nop 0
	v_lshlrev_b32_e32 v74, 16, v90
	v_add_f32_e32 v70, v70, v74
	v_and_b32_e32 v74, 0xffff0000, v90
	v_add_f32_e32 v71, v71, v74
	v_lshlrev_b32_e32 v74, 16, v91
	v_add_f32_e32 v72, v72, v74
	v_and_b32_e32 v74, 0xffff0000, v91
	v_add_f32_e32 v73, v73, v74
	v_lshlrev_b32_e32 v74, 16, v92
	v_add_f32_e32 v74, v66, v74
	v_and_b32_e32 v66, 0xffff0000, v92
	v_add_f32_e32 v75, v67, v66
	v_lshlrev_b32_e32 v66, 16, v93
	v_add_f32_e32 v76, v68, v66
	v_and_b32_e32 v66, 0xffff0000, v93
	v_add_f32_e32 v69, v69, v66
	v_mul_f32_e32 v66, v71, v71
	v_mul_f32_e32 v67, v73, v73
	v_fmac_f32_e32 v66, v70, v70
	v_fmac_f32_e32 v67, v72, v72
	v_add_f32_e32 v66, v66, v67
	v_mul_f32_e32 v67, v75, v75
	v_mul_f32_e32 v68, v69, v69
	v_fmac_f32_e32 v67, v74, v74
	v_fmac_f32_e32 v68, v76, v76
	v_add_f32_e32 v67, v67, v68
	v_add_f32_e32 v66, v66, v67
	v_add_f32_e32 v77, v89, v66
	v_cvt_pk_bf16_f32 v66, v70, v71
	v_cvt_pk_bf16_f32 v67, v72, v73
	v_cvt_pk_bf16_f32 v68, v74, v75
	v_cvt_pk_bf16_f32 v69, v76, v69
	global_store_dwordx4 v[84:85], v[66:69], off offset:256 sc1
	ds_bpermute_b32 v66, v0, v77
	s_waitcnt lgkmcnt(0)
	v_add_f32_e32 v66, v77, v66
	ds_bpermute_b32 v67, v134, v66
	s_waitcnt lgkmcnt(0)
; __device__ __forceinline__ unsigned cvt_pk_bf16(float lo, float hi) { unsigned r; asm volatile("v_cvt_pk_bf16_f32 %0, %1, %2" : "=v"(r) : "v"(lo), "v"(hi)); return r; }
; __device__ __forceinline__ float bflo(unsigned u) { return __uint_as_float(u << 16); }
; __device__ __forceinline__ float bfhi(unsigned u) { return __uint_as_float(u & 0xffff0000u); }
; __device__ __forceinline__ float shfl_xor_l(float v, int mask, int lane) { return __builtin_bit_cast(float, __builtin_amdgcn_ds_bpermute((lane ^ mask) << 2, __builtin_bit_cast(int, v))); }
; template <bool F32OUT>
; __device__ __forceinline__ void res_epi(const f32x4 (&acc)[2][2][4][2], int pm, int pn, int wr, int wc, int fr, int fq, bf16_t* xb, float* xout, float* ssq_next) {
;     ...
;             const int row = row0 + ai * HALF + m * 16;
;             const size_t off = (size_t)row * D + col0;
;             u32x4 r[2];
; #pragma unroll
;             for (int bj = 0; bj < 2; ++bj) r[bj] = *(const u32x4*)(xb + off + bj * HALF);
;             float s = 0.f;
; #pragma unroll
;             for (int bj = 0; bj < 2; ++bj) {
;                 f32x4 v0 = acc[ai][bj][m][0], v1 = acc[ai][bj][m][1];
;                 v0[0] += bflo(r[bj].x); v0[1] += bfhi(r[bj].x); v0[2] += bflo(r[bj].y); v0[3] += bfhi(r[bj].y);
;                 v1[0] += bflo(r[bj].z); v1[1] += bfhi(r[bj].z); v1[2] += bflo(r[bj].w); v1[3] += bfhi(r[bj].w);
;                 if (F32OUT) { *(f32x4*)(xout + off + bj * HALF) = v0; *(f32x4*)(xout + off + bj * HALF + 4) = v1; }
;                 s += ((v0[0] * v0[0] + v0[1] * v0[1]) + (v0[2] * v0[2] + v0[3] * v0[3])) + ((v1[0] * v1[0] + v1[1] * v1[1]) + (v1[2] * v1[2] + v1[3] * v1[3]));
;                 u32x4 w; w.x = cvt_pk_bf16(v0[0], v0[1]); w.y = cvt_pk_bf16(v0[2], v0[3]); w.z = cvt_pk_bf16(v1[0], v1[1]); w.w = cvt_pk_bf16(v1[2], v1[3]);
;                 if (!F32OUT) *(u32x4*)(xb + off + bj * HALF) = w;
;             }
;             if (!F32OUT) { s += shfl_xor_l(s, 16, ln); s += shfl_xor_l(s, 32, ln);
;                 ssq_next[(size_t)row * 32 + pn * 4 + wc] = s; }
	v_add_f32_e32 v68, v66, v67
	v_lshlrev_b64 v[66:67], 7, v[82:83]
	v_lshl_add_u64 v[66:67], s[0:1], 0, v[66:67]
	global_store_dword v[66:67], v68, off
	v_add_u32_e32 v66, 0x80, v130
	v_ashrrev_i32_e32 v67, 31, v66
	v_lshlrev_b64 v[68:69], 12, v[66:67]
	v_lshl_add_u64 v[68:69], s[4:5], 0, v[68:69]
	v_lshl_add_u64 v[68:69], v[68:69], 0, v[132:133]
	global_load_dwordx4 v[70:73], v[68:69], off
	global_load_dwordx4 v[74:77], v[68:69], off offset:256
	s_waitcnt vmcnt(1)
	v_lshlrev_b32_e32 v78, 16, v70
	v_and_b32_e32 v70, 0xffff0000, v70
	v_add_f32_e32 v63, v63, v70
	v_lshlrev_b32_e32 v70, 16, v71
	v_add_f32_e32 v64, v64, v70
	v_and_b32_e32 v70, 0xffff0000, v71
	v_add_f32_e32 v65, v65, v70
	v_lshlrev_b32_e32 v70, 16, v72
	v_add_f32_e32 v70, v58, v70
	v_and_b32_e32 v58, 0xffff0000, v72
	v_add_f32_e32 v71, v59, v58
	v_lshlrev_b32_e32 v58, 16, v73
	v_add_f32_e32 v72, v60, v58
	v_and_b32_e32 v58, 0xffff0000, v73
	v_add_f32_e32 v62, v62, v78
	v_add_f32_e32 v61, v61, v58
	v_mul_f32_e32 v58, v63, v63
	v_mul_f32_e32 v59, v65, v65
	v_fmac_f32_e32 v58, v62, v62
	v_fmac_f32_e32 v59, v64, v64
	v_add_f32_e32 v58, v58, v59
	v_mul_f32_e32 v59, v71, v71
	v_mul_f32_e32 v60, v61, v61
	v_fmac_f32_e32 v59, v70, v70
	v_fmac_f32_e32 v60, v72, v72
	v_add_f32_e32 v59, v59, v60
	v_add_f32_e32 v73, v58, v59
	v_cvt_pk_bf16_f32 v58, v62, v63
	v_cvt_pk_bf16_f32 v59, v64, v65
	v_cvt_pk_bf16_f32 v60, v70, v71
	v_cvt_pk_bf16_f32 v61, v72, v61
	global_store_dwordx4 v[68:69], v[58:61], off sc1
	s_waitcnt vmcnt(1)
	s_nop 0
	v_lshlrev_b32_e32 v58, 16, v74
	v_add_f32_e32 v54, v54, v58
	v_and_b32_e32 v58, 0xffff0000, v74
	v_add_f32_e32 v55, v55, v58
	v_lshlrev_b32_e32 v58, 16, v75
	v_add_f32_e32 v56, v56, v58
	v_and_b32_e32 v58, 0xffff0000, v75
	v_add_f32_e32 v57, v57, v58
	v_lshlrev_b32_e32 v58, 16, v76
	v_add_f32_e32 v58, v50, v58
	v_and_b32_e32 v50, 0xffff0000, v76
	v_add_f32_e32 v59, v51, v50
	v_lshlrev_b32_e32 v50, 16, v77
	v_add_f32_e32 v60, v52, v50
	v_and_b32_e32 v50, 0xffff0000, v77
	v_add_f32_e32 v53, v53, v50
	v_mul_f32_e32 v50, v55, v55
	v_mul_f32_e32 v51, v57, v57
	v_fmac_f32_e32 v50, v54, v54
	v_fmac_f32_e32 v51, v56, v56
	v_add_f32_e32 v50, v50, v51
	v_mul_f32_e32 v51, v59, v59
	v_mul_f32_e32 v52, v53, v53
	v_fmac_f32_e32 v51, v58, v58
	v_fmac_f32_e32 v52, v60, v60
	v_add_f32_e32 v51, v51, v52
	v_add_f32_e32 v50, v50, v51
	v_add_f32_e32 v61, v73, v50
	v_cvt_pk_bf16_f32 v50, v54, v55
	v_cvt_pk_bf16_f32 v51, v56, v57
	v_cvt_pk_bf16_f32 v52, v58, v59
	v_cvt_pk_bf16_f32 v53, v60, v53
	global_store_dwordx4 v[68:69], v[50:53], off offset:256 sc1
	ds_bpermute_b32 v50, v0, v61
	s_waitcnt lgkmcnt(0)
	v_add_f32_e32 v50, v61, v50
	ds_bpermute_b32 v51, v134, v50
	s_waitcnt lgkmcnt(0)
	v_add_f32_e32 v52, v50, v51
	v_lshlrev_b64 v[50:51], 7, v[66:67]
	v_lshl_add_u64 v[50:51], s[0:1], 0, v[50:51]
	global_store_dword v[50:51], v52, off
	v_add_u32_e32 v50, 0x90, v130
	v_ashrrev_i32_e32 v51, 31, v50
	v_lshlrev_b64 v[52:53], 12, v[50:51]
	v_lshl_add_u64 v[52:53], s[4:5], 0, v[52:53]
	v_lshl_add_u64 v[52:53], v[52:53], 0, v[132:133]
	global_load_dwordx4 v[54:57], v[52:53], off
	global_load_dwordx4 v[58:61], v[52:53], off offset:256
	s_waitcnt vmcnt(1)
	v_lshlrev_b32_e32 v62, 16, v54
	v_and_b32_e32 v54, 0xffff0000, v54
	v_add_f32_e32 v47, v47, v54
	v_lshlrev_b32_e32 v54, 16, v55
	v_add_f32_e32 v48, v48, v54
	v_and_b32_e32 v54, 0xffff0000, v55
	v_add_f32_e32 v49, v49, v54
	v_lshlrev_b32_e32 v54, 16, v56
	v_add_f32_e32 v54, v42, v54
	v_and_b32_e32 v42, 0xffff0000, v56
	v_add_f32_e32 v55, v43, v42
	v_lshlrev_b32_e32 v42, 16, v57
	v_add_f32_e32 v56, v44, v42
	v_and_b32_e32 v42, 0xffff0000, v57
	v_add_f32_e32 v46, v46, v62
	v_add_f32_e32 v45, v45, v42
	v_mul_f32_e32 v42, v47, v47
	v_mul_f32_e32 v43, v49, v49
	v_fmac_f32_e32 v42, v46, v46
	v_fmac_f32_e32 v43, v48, v48
	v_add_f32_e32 v42, v42, v43
	v_mul_f32_e32 v43, v55, v55
	v_mul_f32_e32 v44, v45, v45
	v_fmac_f32_e32 v43, v54, v54
	v_fmac_f32_e32 v44, v56, v56
	v_add_f32_e32 v43, v43, v44
	v_add_f32_e32 v57, v42, v43
	v_cvt_pk_bf16_f32 v42, v46, v47
	v_cvt_pk_bf16_f32 v43, v48, v49
	v_cvt_pk_bf16_f32 v44, v54, v55
	v_cvt_pk_bf16_f32 v45, v56, v45
	global_store_dwordx4 v[52:53], v[42:45], off sc1
	s_waitcnt vmcnt(1)
	s_nop 0
	v_lshlrev_b32_e32 v42, 16, v58
	v_add_f32_e32 v38, v38, v42
	v_and_b32_e32 v42, 0xffff0000, v58
	v_add_f32_e32 v39, v39, v42
	v_lshlrev_b32_e32 v42, 16, v59
	v_add_f32_e32 v40, v40, v42
	v_and_b32_e32 v42, 0xffff0000, v59
	v_add_f32_e32 v41, v41, v42
	v_lshlrev_b32_e32 v42, 16, v60
	v_add_f32_e32 v42, v34, v42
	v_and_b32_e32 v34, 0xffff0000, v60
	v_add_f32_e32 v43, v35, v34
	v_lshlrev_b32_e32 v34, 16, v61
	v_add_f32_e32 v44, v36, v34
	v_and_b32_e32 v34, 0xffff0000, v61
	v_add_f32_e32 v37, v37, v34
	v_mul_f32_e32 v34, v39, v39
	v_mul_f32_e32 v35, v41, v41
	v_fmac_f32_e32 v34, v38, v38
	v_fmac_f32_e32 v35, v40, v40
	v_add_f32_e32 v34, v34, v35
	v_mul_f32_e32 v35, v43, v43
	v_mul_f32_e32 v36, v37, v37
	v_fmac_f32_e32 v35, v42, v42
	v_fmac_f32_e32 v36, v44, v44
	v_add_f32_e32 v35, v35, v36
	v_add_f32_e32 v34, v34, v35
	v_add_f32_e32 v45, v57, v34
	v_cvt_pk_bf16_f32 v34, v38, v39
	v_cvt_pk_bf16_f32 v35, v40, v41
	v_cvt_pk_bf16_f32 v36, v42, v43
	v_cvt_pk_bf16_f32 v37, v44, v37
	global_store_dwordx4 v[52:53], v[34:37], off offset:256 sc1
	ds_bpermute_b32 v34, v0, v45
	s_waitcnt lgkmcnt(0)
	v_add_f32_e32 v34, v45, v34
	ds_bpermute_b32 v35, v134, v34
	s_waitcnt lgkmcnt(0)
; __device__ __forceinline__ unsigned cvt_pk_bf16(float lo, float hi) { unsigned r; asm volatile("v_cvt_pk_bf16_f32 %0, %1, %2" : "=v"(r) : "v"(lo), "v"(hi)); return r; }
; __device__ __forceinline__ float bflo(unsigned u) { return __uint_as_float(u << 16); }
; __device__ __forceinline__ float bfhi(unsigned u) { return __uint_as_float(u & 0xffff0000u); }
; __device__ __forceinline__ float shfl_xor_l(float v, int mask, int lane) { return __builtin_bit_cast(float, __builtin_amdgcn_ds_bpermute((lane ^ mask) << 2, __builtin_bit_cast(int, v))); }
; template <bool F32OUT>
; __device__ __forceinline__ void res_epi(const f32x4 (&acc)[2][2][4][2], int pm, int pn, int wr, int wc, int fr, int fq, bf16_t* xb, float* xout, float* ssq_next) {
;     ...
;             const int row = row0 + ai * HALF + m * 16;
;             const size_t off = (size_t)row * D + col0;
;             u32x4 r[2];
; #pragma unroll
;             for (int bj = 0; bj < 2; ++bj) r[bj] = *(const u32x4*)(xb + off + bj * HALF);
;             float s = 0.f;
; #pragma unroll
;             for (int bj = 0; bj < 2; ++bj) {
;                 f32x4 v0 = acc[ai][bj][m][0], v1 = acc[ai][bj][m][1];
;                 v0[0] += bflo(r[bj].x); v0[1] += bfhi(r[bj].x); v0[2] += bflo(r[bj].y); v0[3] += bfhi(r[bj].y);
;                 v1[0] += bflo(r[bj].z); v1[1] += bfhi(r[bj].z); v1[2] += bflo(r[bj].w); v1[3] += bfhi(r[bj].w);
;                 if (F32OUT) { *(f32x4*)(xout + off + bj * HALF) = v0; *(f32x4*)(xout + off + bj * HALF + 4) = v1; }
;                 s += ((v0[0] * v0[0] + v0[1] * v0[1]) + (v0[2] * v0[2] + v0[3] * v0[3])) + ((v1[0] * v1[0] + v1[1] * v1[1]) + (v1[2] * v1[2] + v1[3] * v1[3]));
;                 u32x4 w; w.x = cvt_pk_bf16(v0[0], v0[1]); w.y = cvt_pk_bf16(v0[2], v0[3]); w.z = cvt_pk_bf16(v1[0], v1[1]); w.w = cvt_pk_bf16(v1[2], v1[3]);
;                 if (!F32OUT) *(u32x4*)(xb + off + bj * HALF) = w;
;             }
;             if (!F32OUT) { s += shfl_xor_l(s, 16, ln); s += shfl_xor_l(s, 32, ln);
;                 ssq_next[(size_t)row * 32 + pn * 4 + wc] = s; }
	v_add_f32_e32 v36, v34, v35
	v_lshlrev_b64 v[34:35], 7, v[50:51]
	v_lshl_add_u64 v[34:35], s[0:1], 0, v[34:35]
	global_store_dword v[34:35], v36, off
	v_add_u32_e32 v34, 0xa0, v130
	v_ashrrev_i32_e32 v35, 31, v34
	v_lshlrev_b64 v[36:37], 12, v[34:35]
	v_lshl_add_u64 v[36:37], s[4:5], 0, v[36:37]
	v_lshl_add_u64 v[36:37], v[36:37], 0, v[132:133]
	global_load_dwordx4 v[38:41], v[36:37], off
	global_load_dwordx4 v[42:45], v[36:37], off offset:256
	s_waitcnt vmcnt(1)
	v_lshlrev_b32_e32 v46, 16, v38
	v_and_b32_e32 v38, 0xffff0000, v38
	v_add_f32_e32 v31, v31, v38
	v_lshlrev_b32_e32 v38, 16, v39
	v_add_f32_e32 v32, v32, v38
	v_and_b32_e32 v38, 0xffff0000, v39
	v_add_f32_e32 v33, v33, v38
	v_lshlrev_b32_e32 v38, 16, v40
	v_add_f32_e32 v38, v26, v38
	v_and_b32_e32 v26, 0xffff0000, v40
	v_add_f32_e32 v39, v27, v26
	v_lshlrev_b32_e32 v26, 16, v41
	v_add_f32_e32 v40, v28, v26
	v_and_b32_e32 v26, 0xffff0000, v41
	v_add_f32_e32 v30, v30, v46
	v_add_f32_e32 v29, v29, v26
	v_mul_f32_e32 v26, v31, v31
	v_mul_f32_e32 v27, v33, v33
	v_fmac_f32_e32 v26, v30, v30
	v_fmac_f32_e32 v27, v32, v32
	v_add_f32_e32 v26, v26, v27
	v_mul_f32_e32 v27, v39, v39
	v_mul_f32_e32 v28, v29, v29
	v_fmac_f32_e32 v27, v38, v38
	v_fmac_f32_e32 v28, v40, v40
	v_add_f32_e32 v27, v27, v28
	v_add_f32_e32 v41, v26, v27
	v_cvt_pk_bf16_f32 v26, v30, v31
	v_cvt_pk_bf16_f32 v27, v32, v33
	v_cvt_pk_bf16_f32 v28, v38, v39
	v_cvt_pk_bf16_f32 v29, v40, v29
	global_store_dwordx4 v[36:37], v[26:29], off sc1
	s_waitcnt vmcnt(1)
	s_nop 0
	v_lshlrev_b32_e32 v26, 16, v42
	v_add_f32_e32 v22, v22, v26
	v_and_b32_e32 v26, 0xffff0000, v42
	v_add_f32_e32 v23, v23, v26
	v_lshlrev_b32_e32 v26, 16, v43
	v_add_f32_e32 v24, v24, v26
	v_and_b32_e32 v26, 0xffff0000, v43
	v_add_f32_e32 v25, v25, v26
	v_lshlrev_b32_e32 v26, 16, v44
	v_add_f32_e32 v26, v18, v26
	v_and_b32_e32 v18, 0xffff0000, v44
	v_add_f32_e32 v27, v19, v18
	v_lshlrev_b32_e32 v18, 16, v45
	v_add_f32_e32 v28, v20, v18
	v_and_b32_e32 v18, 0xffff0000, v45
	v_add_f32_e32 v21, v21, v18
	v_mul_f32_e32 v18, v23, v23
	v_mul_f32_e32 v19, v25, v25
	v_fmac_f32_e32 v18, v22, v22
	v_fmac_f32_e32 v19, v24, v24
	v_add_f32_e32 v18, v18, v19
	v_mul_f32_e32 v19, v27, v27
	v_mul_f32_e32 v20, v21, v21
	v_fmac_f32_e32 v19, v26, v26
	v_fmac_f32_e32 v20, v28, v28
	v_add_f32_e32 v19, v19, v20
	v_add_f32_e32 v18, v18, v19
	v_add_f32_e32 v29, v41, v18
	v_cvt_pk_bf16_f32 v18, v22, v23
	v_cvt_pk_bf16_f32 v19, v24, v25
	v_cvt_pk_bf16_f32 v20, v26, v27
	v_cvt_pk_bf16_f32 v21, v28, v21
	global_store_dwordx4 v[36:37], v[18:21], off offset:256 sc1
	ds_bpermute_b32 v18, v0, v29
	s_waitcnt lgkmcnt(0)
	v_add_f32_e32 v18, v29, v18
	ds_bpermute_b32 v19, v134, v18
	s_waitcnt lgkmcnt(0)
	v_add_f32_e32 v20, v18, v19
	v_lshlrev_b64 v[18:19], 7, v[34:35]
	v_lshl_add_u64 v[18:19], s[0:1], 0, v[18:19]
	global_store_dword v[18:19], v20, off
	v_add_u32_e32 v18, 0xb0, v130
	v_ashrrev_i32_e32 v19, 31, v18
	v_lshlrev_b64 v[20:21], 12, v[18:19]
	v_lshl_add_u64 v[20:21], s[4:5], 0, v[20:21]
	v_lshl_add_u64 v[20:21], v[20:21], 0, v[132:133]
	global_load_dwordx4 v[22:25], v[20:21], off
	global_load_dwordx4 v[26:29], v[20:21], off offset:256
	s_waitcnt vmcnt(1)
	v_lshlrev_b32_e32 v30, 16, v22
	v_and_b32_e32 v22, 0xffff0000, v22
	v_add_f32_e32 v15, v15, v22
	v_lshlrev_b32_e32 v22, 16, v23
	v_add_f32_e32 v16, v16, v22
	v_and_b32_e32 v22, 0xffff0000, v23
	v_add_f32_e32 v17, v17, v22
	v_lshlrev_b32_e32 v22, 16, v24
	v_add_f32_e32 v22, v10, v22
	v_and_b32_e32 v10, 0xffff0000, v24
	v_add_f32_e32 v23, v11, v10
	v_lshlrev_b32_e32 v10, 16, v25
	v_add_f32_e32 v24, v12, v10
	v_and_b32_e32 v10, 0xffff0000, v25
	v_add_f32_e32 v14, v14, v30
	v_add_f32_e32 v13, v13, v10
	v_mul_f32_e32 v10, v15, v15
	v_mul_f32_e32 v11, v17, v17
	v_fmac_f32_e32 v10, v14, v14
	v_fmac_f32_e32 v11, v16, v16
	v_add_f32_e32 v10, v10, v11
	v_mul_f32_e32 v11, v23, v23
	v_mul_f32_e32 v12, v13, v13
	v_fmac_f32_e32 v11, v22, v22
	v_fmac_f32_e32 v12, v24, v24
	v_add_f32_e32 v11, v11, v12
	v_add_f32_e32 v25, v10, v11
	v_cvt_pk_bf16_f32 v10, v14, v15
	v_cvt_pk_bf16_f32 v11, v16, v17
	v_cvt_pk_bf16_f32 v12, v22, v23
	v_cvt_pk_bf16_f32 v13, v24, v13
	global_store_dwordx4 v[20:21], v[10:13], off sc1
	s_waitcnt vmcnt(1)
	s_nop 0
	v_lshlrev_b32_e32 v10, 16, v26
	v_add_f32_e32 v6, v6, v10
	v_and_b32_e32 v10, 0xffff0000, v26
	v_add_f32_e32 v7, v7, v10
	v_lshlrev_b32_e32 v10, 16, v27
	v_add_f32_e32 v8, v8, v10
	v_and_b32_e32 v10, 0xffff0000, v27
	v_add_f32_e32 v9, v9, v10
	v_lshlrev_b32_e32 v10, 16, v28
	v_add_f32_e32 v10, v2, v10
	v_and_b32_e32 v2, 0xffff0000, v28
	v_add_f32_e32 v11, v3, v2
	v_lshlrev_b32_e32 v2, 16, v29
	v_add_f32_e32 v12, v4, v2
	v_and_b32_e32 v2, 0xffff0000, v29
	v_add_f32_e32 v5, v5, v2
	v_mul_f32_e32 v2, v7, v7
	v_mul_f32_e32 v3, v9, v9
	v_fmac_f32_e32 v2, v6, v6
	v_fmac_f32_e32 v3, v8, v8
	v_add_f32_e32 v2, v2, v3
	v_mul_f32_e32 v3, v11, v11
	v_mul_f32_e32 v4, v5, v5
	v_fmac_f32_e32 v3, v10, v10
	v_fmac_f32_e32 v4, v12, v12
	v_add_f32_e32 v3, v3, v4
	v_add_f32_e32 v2, v2, v3
	v_add_f32_e32 v13, v25, v2
	ds_bpermute_b32 v0, v0, v13
	v_cvt_pk_bf16_f32 v2, v6, v7
	v_cvt_pk_bf16_f32 v3, v8, v9
	v_cvt_pk_bf16_f32 v4, v10, v11
	v_cvt_pk_bf16_f32 v5, v12, v5
	s_waitcnt lgkmcnt(0)
	v_add_f32_e32 v0, v13, v0
	global_store_dwordx4 v[20:21], v[2:5], off offset:256 sc1
	ds_bpermute_b32 v2, v134, v0
	s_waitcnt lgkmcnt(0)
	v_add_f32_e32 v0, v0, v2
	v_lshlrev_b64 v[2:3], 7, v[18:19]
	v_lshl_add_u64 v[2:3], s[0:1], 0, v[2:3]
	global_store_dword v[2:3], v0, off
